# odd row panels start 8 us late after the mixer-to-W_out global barrier so one half's HBM-bound residual epilogues run beside the other half's K loops
# baseline (speedup 1.0000x reference)
; __global__ void __launch_bounds__(512, 2) fwd_kernel(Args A_unused) {
;     ...
;     for (int ph = ph_lo; ph < ph_hi; ++ph) {
;         CA* P = P0; asm volatile("" : "+s"(P)); CA& A = *P;
;         bf16_t* XN = (bf16_t*)(A.ws + WS_XN); bf16_t* ACT = (bf16_t*)(A.ws + WS_ACT); bf16_t* Zp = (bf16_t*)(A.ws + WS_Z); bf16_t* MIXp = (bf16_t*)(A.ws + WS_MIX);
;         const float* MOD = (const float*)(A.ws + WS_MOD);
;         if (ph == 0) { p0_prologue(A, lds); }
;         else if (ph == 1) { p1_phase(A); }
;         else {
;             int l = (ph - 2) / 7, s = (ph - 2) % 7;
;             asm volatile("" : "+s"(l), "+s"(s));
;             if (s == 3) { cum_scan(A, l, lds); mix_phase(A, l, lds); }
;             else {
;                 const bf16_t* Ap; const bf16_t* Bt; int N, K; EpiAll E{(const void*)P0, l, s};
;                 if (s == 0 || s == 5) { Ap = XN; Bt = (const bf16_t*)(A.ws + (s == 0 ? WS_W1IN : WS_W2IN)) + (size_t)l * 2 * DFF * DM; N = 2 * DFF; K = DM; }
;                 else if (s == 2) { Ap = XN; Bt = (const bf16_t*)(A.ws + WS_WIN) + (size_t)l * ZN * DM; N = ZN; K = DM; }
;                 else { Ap = (s == 4) ? MIXp : ACT;
;                     Bt = (s == 4) ? (const bf16_t*)(A.ws + WS_WOUT) + (size_t)l * DM * DM : (const bf16_t*)(A.ws + (s == 1 ? WS_W1OUT : WS_W2OUT)) + (size_t)l * DM * DFF;
;                     N = DM; K = (s == 4) ? DM : DFF; }
;                 pg8::Gemm g{Ap, Bt, M, N, K}; pg8::StaticOrder S; S.init(M, N, (int)gridDim.x, (int)blockIdx.x);
;                 pg8::gemm_phase<EpiAll, pg8::StaticOrder, true, true>(lds, g, S, E);
;                 if (s == 1 || s == 4 || s == 6) fused_norm_tail(A, l, s);
.LBB0_8:
	s_or_b64 exec, exec, s[4:5]
	s_waitcnt lgkmcnt(0)
	v_readlane_b32 s6, v238, 0
	v_readlane_b32 s8, v237, 62
	s_cmp_eq_u32 s6, 6
	s_cselect_b32 s7, 1, 0
	s_cmp_eq_u32 s6, 13
	s_cselect_b32 s7, 1, s7
	s_bfe_u32 s8, s8, 0x10003
	s_and_b32 s7, s7, s8
	s_cmp_eq_u32 s7, 0
	s_cbranch_scc1 .Lmy_nodelay
	s_sleep 127
	s_sleep 127
.Lmy_nodelay:
	s_barrier
	s_mov_b64 s[4:5], 0
